# latent-attention items: the latent scans' CU-partner workgroups take one item each, the 128 second-round items go to workgroups 384..511 (less LDS traffic next to the LDS-bound latent scans)
# speedup vs baseline: 1.0138x; 1.0138x over previous
.Lat_la_next:
	s_sub_u32 s15, s15, 1
	s_cmp_lg_u32 s15, 0
	s_cbranch_scc1 .Lat_la_tile
	v_readlane_b32 s100, v224, 34
	v_readlane_b32 s101, v224, 35
	v_mov_b32_e32 v125, v123
	s_load_dwordx2 s[20:21], s[100:101], 0x160
	s_nop 0
	v_permlane32_swap_b32_e32 v125, v123
	v_add_f32_e32 v123, v123, v125
	v_rcp_f32_e32 v128, v123
	v_readfirstlane_b32 s51, v131
	s_and_b32 s2, s50, 1
	s_lshr_b32 s51, s51, 6
	s_lshl_b32 s2, s2, 2
	s_add_i32 s2, s2, s51
	s_lshl_b32 s2, s2, 7
	s_bfe_u32 s3, s50, 0x60001
	s_lshr_b32 s14, s50, 7
	s_lshl_b32 s14, s14, 11
	s_addk_i32 s14, 0x1000
	s_lshl_b32 s3, s3, 5
	s_add_i32 s3, s3, s14
	v_and_b32_e32 v0, 31, v131
	v_add_u32_e32 v0, s3, v0
	v_lshlrev_b32_e32 v0, 11, v0
	v_bfe_u32 v134, v131, 5, 1
	v_lshl_add_u32 v0, v134, 3, v0
	v_add_u32_e32 v0, s2, v0
	s_nop 8
	v_pk_mul_f32 v[18:19], v[18:19], v[128:129] op_sel_hi:[1,0]
	v_pk_mul_f32 v[34:35], v[34:35], v[128:129] op_sel_hi:[1,0]
	v_pk_mul_f32 v[20:21], v[20:21], v[128:129] op_sel_hi:[1,0]
	v_pk_mul_f32 v[36:37], v[36:37], v[128:129] op_sel_hi:[1,0]
	v_pk_mul_f32 v[22:23], v[22:23], v[128:129] op_sel_hi:[1,0]
	v_pk_mul_f32 v[38:39], v[38:39], v[128:129] op_sel_hi:[1,0]
	v_pk_mul_f32 v[24:25], v[24:25], v[128:129] op_sel_hi:[1,0]
	v_pk_mul_f32 v[40:41], v[40:41], v[128:129] op_sel_hi:[1,0]
	v_pk_mul_f32 v[26:27], v[26:27], v[128:129] op_sel_hi:[1,0]
	v_pk_mul_f32 v[42:43], v[42:43], v[128:129] op_sel_hi:[1,0]
	v_pk_mul_f32 v[28:29], v[28:29], v[128:129] op_sel_hi:[1,0]
	v_pk_mul_f32 v[44:45], v[44:45], v[128:129] op_sel_hi:[1,0]
	v_pk_mul_f32 v[30:31], v[30:31], v[128:129] op_sel_hi:[1,0]
	v_pk_mul_f32 v[46:47], v[46:47], v[128:129] op_sel_hi:[1,0]
	v_pk_mul_f32 v[32:33], v[32:33], v[128:129] op_sel_hi:[1,0]
	v_pk_mul_f32 v[48:49], v[48:49], v[128:129] op_sel_hi:[1,0]
	v_cvt_pk_f16_f32 v50, v18, v19
	v_cvt_pk_f16_f32 v58, v34, v35
	v_cvt_pk_f16_f32 v51, v20, v21
	v_cvt_pk_f16_f32 v59, v36, v37
	v_cvt_pk_f16_f32 v52, v22, v23
	v_cvt_pk_f16_f32 v60, v38, v39
	v_cvt_pk_f16_f32 v53, v24, v25
	v_cvt_pk_f16_f32 v61, v40, v41
	v_cvt_pk_f16_f32 v54, v26, v27
	v_cvt_pk_f16_f32 v62, v42, v43
	v_cvt_pk_f16_f32 v55, v28, v29
	v_cvt_pk_f16_f32 v63, v44, v45
	v_cvt_pk_f16_f32 v56, v30, v31
	v_cvt_pk_f16_f32 v64, v46, v47
	v_cvt_pk_f16_f32 v57, v32, v33
	v_cvt_pk_f16_f32 v65, v48, v49
	s_waitcnt lgkmcnt(0)
	global_store_dwordx2 v0, v[50:51], s[20:21] offset:0
	global_store_dwordx2 v0, v[58:59], s[20:21] offset:64
	global_store_dwordx2 v0, v[52:53], s[20:21] offset:16
	global_store_dwordx2 v0, v[60:61], s[20:21] offset:80
	global_store_dwordx2 v0, v[54:55], s[20:21] offset:32
	global_store_dwordx2 v0, v[62:63], s[20:21] offset:96
	global_store_dwordx2 v0, v[56:57], s[20:21] offset:48
	global_store_dwordx2 v0, v[64:65], s[20:21] offset:112
	s_waitcnt vmcnt(0)
	v_readlane_b32 s101, v224, 3
	s_movk_i32 s100, 0x180
	s_cmpk_lt_u32 s101, 0x80
	s_cselect_b32 s100, 0x200, s100
	s_cmpk_gt_u32 s101, 0xff
	s_cselect_b32 s100, 0x80, s100
	s_add_i32 s50, s50, s100
	s_cmpk_gt_i32 s50, 0x1ff
	s_cbranch_scc0 .LBB0_227
